# P6: sc/sh modulation vectors loaded once per row pair (both rows share the batch-16 group) and sample-row tail loads batched
# speedup vs baseline: 1.0180x; 1.0017x over previous
; __device__ __forceinline__ void norm_apply(const f32x4 (&v)[4], const float* g, const float* sc, const float* sh, bf16_t* orow, int lane) {
;     ...
;     for (int j = 0; j < 4; ++j) { const int c4 = lane + 64 * j;
;         const f32x4 gg = *((const f32x4*)g + c4), cc = *((const f32x4*)sc + c4), hh = *((const f32x4*)sh + c4);
; __global__ void __launch_bounds__(512, 2) mega_fwd(Args a) {
;     ...
;         int row = bx * 8 + wid; f32x4 nv[4];
;         if (row < MP) row_load_bf16(X1B + (size_t)row * DM, nv, lane);
;         for (; row < MP; row += G * 8) {
;             f32x4 v[4];
; #pragma unroll
;             for (int j = 0; j < 4; ++j) v[j] = nv[j];
;             const int nr = row + G * 8;
;             if (nr < MP) row_load_bf16(X1B + (size_t)nr * DM, nv, lane);
;             const int b16 = row >> 12;
;             norm_apply(v, norm2_g, MOD + (size_t)b16 * 6144 + 4096, MOD + (size_t)b16 * 6144 + 3072, Hb + (size_t)row * DM, lane);
.LBB0_1100:
	s_or_b64 exec, exec, s[0:1]
	s_waitcnt lgkmcnt(0)
	v_mov_b32_e32 v0, v211
	s_barrier
	s_nop 0
	v_readfirstlane_b32 s0, v0
	s_ashr_i32 s7, s0, 6
	v_readlane_b32 s0, v238, 46
	v_and_b32_e32 v4, 63, v0
	s_add_i32 s26, s7, s0
	s_cmpk_gt_i32 s26, 0x7fff
	v_lshlrev_b32_e32 v10, 3, v4
	v_lshlrev_b32_e32 v0, 4, v4
	v_or_b32_e32 v6, 64, v4
	s_cbranch_scc1 .LBB0_1105
	v_readlane_b32 s46, v238, 30
	v_readlane_b32 s47, v238, 31
	v_lshlrev_b32_e32 v1, 5, v4
	v_xor_b32_e32 v2, 1, v4
	v_lshlrev_b32_e32 v2, 2, v2
	v_xor_b32_e32 v3, 2, v4
	v_lshlrev_b32_e32 v3, 2, v3
	v_xor_b32_e32 v5, 4, v4
	v_lshlrev_b32_e32 v5, 2, v5
	v_xor_b32_e32 v7, 8, v4
	v_lshlrev_b32_e32 v7, 2, v7
	v_xor_b32_e32 v8, 16, v4
	v_lshlrev_b32_e32 v8, 2, v8
	v_xor_b32_e32 v9, 32, v4
	v_lshlrev_b32_e32 v9, 2, v9
	global_load_dwordx4 v[16:19], v1, s[46:47]
	global_load_dwordx4 v[20:23], v1, s[46:47] offset:16
	global_load_dwordx4 v[24:27], v1, s[46:47] offset:2048
	global_load_dwordx4 v[28:31], v1, s[46:47] offset:2064
	s_lshr_b32 s23, s26, 12
	s_mul_i32 s23, s23, 0x6000
	s_add_u32 s8, s30, s23
	s_addc_u32 s9, s31, 0
	s_add_u32 s10, s8, 0x4000
	s_addc_u32 s11, s9, 0
	s_add_u32 s8, s8, 0x3000
	s_addc_u32 s9, s9, 0
	global_load_dwordx4 v[32:35], v1, s[10:11]
	global_load_dwordx4 v[36:39], v1, s[10:11] offset:16
	global_load_dwordx4 v[40:43], v1, s[10:11] offset:2048
	global_load_dwordx4 v[44:47], v1, s[10:11] offset:2064
	global_load_dwordx4 v[48:51], v1, s[8:9]
	global_load_dwordx4 v[52:55], v1, s[8:9] offset:16
	global_load_dwordx4 v[56:59], v1, s[8:9] offset:2048
	global_load_dwordx4 v[60:63], v1, s[8:9] offset:2064
	s_lshl_b32 s0, s26, 11
	s_add_u32 s0, s4, s0
	s_addc_u32 s1, s5, 0
	global_load_dwordx4 v[96:99], v0, s[0:1]
	global_load_dwordx4 v[100:103], v0, s[0:1] offset:1024
	s_add_i32 s22, s26, s88
	s_min_i32 s22, s22, 0x7fff
	s_lshl_b32 s0, s22, 11
	s_add_u32 s0, s4, s0
	s_addc_u32 s1, s5, 0
	global_load_dwordx4 v[104:107], v0, s[0:1]
	global_load_dwordx4 v[108:111], v0, s[0:1] offset:1024
	s_add_i32 s22, s26, s88
	s_add_i32 s22, s22, s88
	s_min_i32 s22, s22, 0x7fff
	s_lshr_b32 s23, s22, 12
	s_mul_i32 s23, s23, 0x6000
	s_add_u32 s8, s30, s23
	s_addc_u32 s9, s31, 0
	s_add_u32 s10, s8, 0x4000
	s_addc_u32 s11, s9, 0
	s_add_u32 s8, s8, 0x3000
	s_addc_u32 s9, s9, 0
	global_load_dwordx4 v[64:67], v1, s[10:11]
	global_load_dwordx4 v[68:71], v1, s[10:11] offset:16
	global_load_dwordx4 v[72:75], v1, s[10:11] offset:2048
	global_load_dwordx4 v[76:79], v1, s[10:11] offset:2064
	global_load_dwordx4 v[80:83], v1, s[8:9]
	global_load_dwordx4 v[84:87], v1, s[8:9] offset:16
	global_load_dwordx4 v[88:91], v1, s[8:9] offset:2048
	global_load_dwordx4 v[92:95], v1, s[8:9] offset:2064
	s_waitcnt vmcnt(10)
	s_branch .Lp6_e0_go
.Lp6_e0:
	s_add_i32 s22, s26, s88
	s_add_i32 s22, s22, s88
	s_min_i32 s22, s22, 0x7fff
	s_lshr_b32 s23, s22, 12
	s_mul_i32 s23, s23, 0x6000
	s_add_u32 s8, s30, s23
	s_addc_u32 s9, s31, 0
	s_add_u32 s10, s8, 0x4000
	s_addc_u32 s11, s9, 0
	s_add_u32 s8, s8, 0x3000
	s_addc_u32 s9, s9, 0
	global_load_dwordx4 v[64:67], v1, s[10:11]
	global_load_dwordx4 v[68:71], v1, s[10:11] offset:16
	global_load_dwordx4 v[72:75], v1, s[10:11] offset:2048
	global_load_dwordx4 v[76:79], v1, s[10:11] offset:2064
	global_load_dwordx4 v[80:83], v1, s[8:9]
	global_load_dwordx4 v[84:87], v1, s[8:9] offset:16
	global_load_dwordx4 v[88:91], v1, s[8:9] offset:2048
	global_load_dwordx4 v[92:95], v1, s[8:9] offset:2064
	s_waitcnt vmcnt(14)

; __device__ __forceinline__ unsigned cvt_pk_bf16(float lo, float hi) { unsigned r; asm("v_cvt_pk_bf16_f32 %0, %1, %2" : "=v"(r) : "v"(lo), "v"(hi)); return r; }
; __device__ __forceinline__ void norm_apply(const f32x4 (&v)[4], const float* g, const float* sc, const float* sh, bf16_t* orow, int lane) {
;     float s = 0.f;
; #pragma unroll
;     for (int j = 0; j < 4; ++j) s += (v[j][0] * v[j][0] + v[j][1] * v[j][1]) + (v[j][2] * v[j][2] + v[j][3] * v[j][3]);
;     const float rstd = rsqrtf(wave_sum(s) * (1.f / 1024.f) + EPS);
; #pragma unroll
;     for (int j = 0; j < 4; ++j) { const int c4 = lane + 64 * j;
;         const f32x4 gg = *((const f32x4*)g + c4), cc = *((const f32x4*)sc + c4), hh = *((const f32x4*)sh + c4);
;         const f32x4 h = v[j] * rstd * gg * (cc + 1.f) + hh;
;         u32x2 w; w.x = cvt_pk_bf16(h[0], h[1]); w.y = cvt_pk_bf16(h[2], h[3]);
;         *((u32x2*)orow + c4) = w; }
; }
.Lp6_o0:
	s_waitcnt vmcnt(12)
.Lp6_o0_go:
	v_lshlrev_b32_e32 v120, 16, v104
	v_and_b32_e32 v121, 0xffff0000, v104
	v_lshlrev_b32_e32 v122, 16, v105
	v_and_b32_e32 v123, 0xffff0000, v105
	v_lshlrev_b32_e32 v124, 16, v106
	v_and_b32_e32 v125, 0xffff0000, v106
	v_lshlrev_b32_e32 v126, 16, v107
	v_and_b32_e32 v127, 0xffff0000, v107
	v_lshlrev_b32_e32 v128, 16, v108
	v_and_b32_e32 v129, 0xffff0000, v108
	v_lshlrev_b32_e32 v130, 16, v109
	v_and_b32_e32 v131, 0xffff0000, v109
	v_lshlrev_b32_e32 v132, 16, v110
	v_and_b32_e32 v133, 0xffff0000, v110
	v_lshlrev_b32_e32 v134, 16, v111
	v_and_b32_e32 v135, 0xffff0000, v111
	s_add_i32 s22, s26, s88
	s_add_i32 s22, s22, s88
	s_min_i32 s22, s22, 0x7fff
	s_lshl_b32 s0, s22, 11
	s_add_u32 s0, s4, s0
	s_addc_u32 s1, s5, 0
	global_load_dwordx4 v[104:107], v0, s[0:1]
	global_load_dwordx4 v[108:111], v0, s[0:1] offset:1024
	v_mul_f32_e32 v11, v120, v120
	v_mul_f32_e32 v12, v121, v121
	v_fmac_f32_e32 v11, v122, v122
	v_fmac_f32_e32 v12, v123, v123
	v_fmac_f32_e32 v11, v124, v124
	v_fmac_f32_e32 v12, v125, v125
	v_fmac_f32_e32 v11, v126, v126
	v_fmac_f32_e32 v12, v127, v127
	v_fmac_f32_e32 v11, v128, v128
	v_fmac_f32_e32 v12, v129, v129
	v_fmac_f32_e32 v11, v130, v130
	v_fmac_f32_e32 v12, v131, v131
	v_fmac_f32_e32 v11, v132, v132
	v_fmac_f32_e32 v12, v133, v133
	v_fmac_f32_e32 v11, v134, v134
	v_fmac_f32_e32 v12, v135, v135
	v_add_f32_e32 v11, v11, v12
	ds_bpermute_b32 v12, v2, v11
	s_waitcnt lgkmcnt(0)
	v_add_f32_e32 v11, v11, v12
	ds_bpermute_b32 v12, v3, v11
	s_waitcnt lgkmcnt(0)
	v_add_f32_e32 v11, v11, v12
	ds_bpermute_b32 v12, v5, v11
	s_waitcnt lgkmcnt(0)
	v_add_f32_e32 v11, v11, v12
	ds_bpermute_b32 v12, v7, v11
	s_waitcnt lgkmcnt(0)
	v_add_f32_e32 v11, v11, v12
	ds_bpermute_b32 v12, v8, v11
	s_waitcnt lgkmcnt(0)
	v_add_f32_e32 v11, v11, v12
	ds_bpermute_b32 v12, v9, v11
	s_waitcnt lgkmcnt(0)
	v_add_f32_e32 v11, v11, v12
	v_mov_b32_e32 v12, 0x358637bd
	v_fmac_f32_e32 v12, 0x3a800000, v11
	v_rsq_f32_e32 v13, v12
	s_nop 0
	s_lshl_b32 s12, s26, 11
	s_add_u32 s12, s30, s12
	s_addc_u32 s13, s31, 0
	s_add_u32 s12, s12, 0x1d00000
	s_addc_u32 s13, s13, 0
	v_mul_f32_e32 v120, v13, v120
	v_mul_f32_e32 v121, v13, v121
	v_mul_f32_e32 v122, v13, v122
	v_mul_f32_e32 v123, v13, v123
	v_mul_f32_e32 v124, v13, v124
	v_mul_f32_e32 v125, v13, v125
	v_mul_f32_e32 v126, v13, v126
	v_mul_f32_e32 v127, v13, v127
	v_mul_f32_e32 v128, v13, v128
	v_mul_f32_e32 v129, v13, v129
	v_mul_f32_e32 v130, v13, v130
	v_mul_f32_e32 v131, v13, v131
	v_mul_f32_e32 v132, v13, v132
	v_mul_f32_e32 v133, v13, v133
	v_mul_f32_e32 v134, v13, v134
	v_mul_f32_e32 v135, v13, v135
	v_mul_f32_e32 v120, v16, v120
	v_mul_f32_e32 v121, v17, v121
	v_mul_f32_e32 v122, v18, v122
	v_mul_f32_e32 v123, v19, v123
	v_mul_f32_e32 v124, v20, v124
	v_mul_f32_e32 v125, v21, v125
	v_mul_f32_e32 v126, v22, v126
	v_mul_f32_e32 v127, v23, v127
	v_mul_f32_e32 v128, v24, v128
	v_mul_f32_e32 v129, v25, v129
	v_mul_f32_e32 v130, v26, v130
	v_mul_f32_e32 v131, v27, v131
	v_mul_f32_e32 v132, v28, v132
	v_mul_f32_e32 v133, v29, v133
	v_mul_f32_e32 v134, v30, v134
	v_mul_f32_e32 v135, v31, v135
	v_fma_f32 v120, v32, v120, v48
	v_fma_f32 v121, v33, v121, v49
	v_fma_f32 v122, v34, v122, v50
	v_fma_f32 v123, v35, v123, v51
	v_fma_f32 v124, v36, v124, v52
	v_fma_f32 v125, v37, v125, v53
	v_fma_f32 v126, v38, v126, v54
	v_fma_f32 v127, v39, v127, v55
	v_fma_f32 v128, v40, v128, v56
	v_fma_f32 v129, v41, v129, v57
	v_fma_f32 v130, v42, v130, v58
	v_fma_f32 v131, v43, v131, v59
	v_fma_f32 v132, v44, v132, v60
	v_fma_f32 v133, v45, v133, v61
	v_fma_f32 v134, v46, v134, v62
	v_fma_f32 v135, v47, v135, v63
	v_cvt_pk_bf16_f32 v120, v120, v121
	v_cvt_pk_bf16_f32 v121, v122, v123
	v_cvt_pk_bf16_f32 v122, v124, v125
	v_cvt_pk_bf16_f32 v123, v126, v127
	v_cvt_pk_bf16_f32 v124, v128, v129
	v_cvt_pk_bf16_f32 v125, v130, v131
	v_cvt_pk_bf16_f32 v126, v132, v133
	v_cvt_pk_bf16_f32 v127, v134, v135
	global_store_dwordx4 v0, v[120:123], s[12:13]
	global_store_dwordx4 v0, v[124:127], s[12:13] offset:1024
	s_add_i32 s26, s26, s88
	s_cmpk_gt_i32 s26, 0x7fff
	s_cbranch_scc1 .Lp6_done
.Lp6_e1:
	s_add_i32 s22, s26, s88
	s_add_i32 s22, s22, s88
	s_min_i32 s22, s22, 0x7fff
	s_lshr_b32 s23, s22, 12
	s_mul_i32 s23, s23, 0x6000
	s_add_u32 s8, s30, s23
	s_addc_u32 s9, s31, 0
	s_add_u32 s10, s8, 0x4000
	s_addc_u32 s11, s9, 0
	s_add_u32 s8, s8, 0x3000
	s_addc_u32 s9, s9, 0
	global_load_dwordx4 v[32:35], v1, s[10:11]
	global_load_dwordx4 v[36:39], v1, s[10:11] offset:16
	global_load_dwordx4 v[40:43], v1, s[10:11] offset:2048
	global_load_dwordx4 v[44:47], v1, s[10:11] offset:2064
	global_load_dwordx4 v[48:51], v1, s[8:9]
	global_load_dwordx4 v[52:55], v1, s[8:9] offset:16
	global_load_dwordx4 v[56:59], v1, s[8:9] offset:2048
	global_load_dwordx4 v[60:63], v1, s[8:9] offset:2064
	s_waitcnt vmcnt(14)
; __device__ __forceinline__ unsigned cvt_pk_bf16(float lo, float hi) { unsigned r; asm("v_cvt_pk_bf16_f32 %0, %1, %2" : "=v"(r) : "v"(lo), "v"(hi)); return r; }
; __device__ __forceinline__ void norm_apply(const f32x4 (&v)[4], const float* g, const float* sc, const float* sh, bf16_t* orow, int lane) {
;     float s = 0.f;
; #pragma unroll
;     for (int j = 0; j < 4; ++j) s += (v[j][0] * v[j][0] + v[j][1] * v[j][1]) + (v[j][2] * v[j][2] + v[j][3] * v[j][3]);
;     const float rstd = rsqrtf(wave_sum(s) * (1.f / 1024.f) + EPS);
; #pragma unroll
;     for (int j = 0; j < 4; ++j) { const int c4 = lane + 64 * j;
;         const f32x4 gg = *((const f32x4*)g + c4), cc = *((const f32x4*)sc + c4), hh = *((const f32x4*)sh + c4);
;         const f32x4 h = v[j] * rstd * gg * (cc + 1.f) + hh;
;         u32x2 w; w.x = cvt_pk_bf16(h[0], h[1]); w.y = cvt_pk_bf16(h[2], h[3]);
;         *((u32x2*)orow + c4) = w; }
; }
.Lp6_e1_go:
	v_lshlrev_b32_e32 v120, 16, v96
	v_and_b32_e32 v121, 0xffff0000, v96
	v_lshlrev_b32_e32 v122, 16, v97
	v_and_b32_e32 v123, 0xffff0000, v97
	v_lshlrev_b32_e32 v124, 16, v98
	v_and_b32_e32 v125, 0xffff0000, v98
	v_lshlrev_b32_e32 v126, 16, v99
	v_and_b32_e32 v127, 0xffff0000, v99
	v_lshlrev_b32_e32 v128, 16, v100
	v_and_b32_e32 v129, 0xffff0000, v100
	v_lshlrev_b32_e32 v130, 16, v101
	v_and_b32_e32 v131, 0xffff0000, v101
	v_lshlrev_b32_e32 v132, 16, v102
	v_and_b32_e32 v133, 0xffff0000, v102
	v_lshlrev_b32_e32 v134, 16, v103
	v_and_b32_e32 v135, 0xffff0000, v103
	s_add_i32 s22, s26, s88
	s_add_i32 s22, s22, s88
	s_min_i32 s22, s22, 0x7fff
	s_lshl_b32 s0, s22, 11
	s_add_u32 s0, s4, s0
	s_addc_u32 s1, s5, 0
	global_load_dwordx4 v[96:99], v0, s[0:1]
	global_load_dwordx4 v[100:103], v0, s[0:1] offset:1024
	v_mul_f32_e32 v11, v120, v120
	v_mul_f32_e32 v12, v121, v121
	v_fmac_f32_e32 v11, v122, v122
	v_fmac_f32_e32 v12, v123, v123
	v_fmac_f32_e32 v11, v124, v124
	v_fmac_f32_e32 v12, v125, v125
	v_fmac_f32_e32 v11, v126, v126
	v_fmac_f32_e32 v12, v127, v127
	v_fmac_f32_e32 v11, v128, v128
	v_fmac_f32_e32 v12, v129, v129
	v_fmac_f32_e32 v11, v130, v130
	v_fmac_f32_e32 v12, v131, v131
	v_fmac_f32_e32 v11, v132, v132
	v_fmac_f32_e32 v12, v133, v133
	v_fmac_f32_e32 v11, v134, v134
	v_fmac_f32_e32 v12, v135, v135
	v_add_f32_e32 v11, v11, v12
	ds_bpermute_b32 v12, v2, v11
	s_waitcnt lgkmcnt(0)
	v_add_f32_e32 v11, v11, v12
	ds_bpermute_b32 v12, v3, v11
	s_waitcnt lgkmcnt(0)
	v_add_f32_e32 v11, v11, v12
	ds_bpermute_b32 v12, v5, v11
	s_waitcnt lgkmcnt(0)
	v_add_f32_e32 v11, v11, v12
	ds_bpermute_b32 v12, v7, v11
	s_waitcnt lgkmcnt(0)
	v_add_f32_e32 v11, v11, v12
	ds_bpermute_b32 v12, v8, v11
	s_waitcnt lgkmcnt(0)
	v_add_f32_e32 v11, v11, v12
	ds_bpermute_b32 v12, v9, v11
	s_waitcnt lgkmcnt(0)
	v_add_f32_e32 v11, v11, v12
	v_mov_b32_e32 v12, 0x358637bd
	v_fmac_f32_e32 v12, 0x3a800000, v11
	v_rsq_f32_e32 v13, v12
	s_nop 0
	s_lshl_b32 s12, s26, 11
	s_add_u32 s12, s30, s12
	s_addc_u32 s13, s31, 0
	s_add_u32 s12, s12, 0x1d00000
	s_addc_u32 s13, s13, 0
	v_mul_f32_e32 v120, v13, v120
	v_mul_f32_e32 v121, v13, v121
	v_mul_f32_e32 v122, v13, v122
	v_mul_f32_e32 v123, v13, v123
	v_mul_f32_e32 v124, v13, v124
	v_mul_f32_e32 v125, v13, v125
	v_mul_f32_e32 v126, v13, v126
	v_mul_f32_e32 v127, v13, v127
	v_mul_f32_e32 v128, v13, v128
	v_mul_f32_e32 v129, v13, v129
	v_mul_f32_e32 v130, v13, v130
	v_mul_f32_e32 v131, v13, v131
	v_mul_f32_e32 v132, v13, v132
	v_mul_f32_e32 v133, v13, v133
	v_mul_f32_e32 v134, v13, v134
	v_mul_f32_e32 v135, v13, v135
	v_mul_f32_e32 v120, v16, v120
	v_mul_f32_e32 v121, v17, v121
	v_mul_f32_e32 v122, v18, v122
	v_mul_f32_e32 v123, v19, v123
	v_mul_f32_e32 v124, v20, v124
	v_mul_f32_e32 v125, v21, v125
	v_mul_f32_e32 v126, v22, v126
	v_mul_f32_e32 v127, v23, v127
	v_mul_f32_e32 v128, v24, v128
	v_mul_f32_e32 v129, v25, v129
	v_mul_f32_e32 v130, v26, v130
	v_mul_f32_e32 v131, v27, v131
	v_mul_f32_e32 v132, v28, v132
	v_mul_f32_e32 v133, v29, v133
	v_mul_f32_e32 v134, v30, v134
	v_mul_f32_e32 v135, v31, v135
	v_add_f32_e32 v64, 1.0, v64
	v_add_f32_e32 v65, 1.0, v65
	v_add_f32_e32 v66, 1.0, v66
	v_add_f32_e32 v67, 1.0, v67
	v_add_f32_e32 v68, 1.0, v68
	v_add_f32_e32 v69, 1.0, v69
	v_add_f32_e32 v70, 1.0, v70
	v_add_f32_e32 v71, 1.0, v71
	v_add_f32_e32 v72, 1.0, v72
	v_add_f32_e32 v73, 1.0, v73
	v_add_f32_e32 v74, 1.0, v74
	v_add_f32_e32 v75, 1.0, v75
	v_add_f32_e32 v76, 1.0, v76
	v_add_f32_e32 v77, 1.0, v77
	v_add_f32_e32 v78, 1.0, v78
	v_add_f32_e32 v79, 1.0, v79
	v_fma_f32 v120, v64, v120, v80
	v_fma_f32 v121, v65, v121, v81
	v_fma_f32 v122, v66, v122, v82
	v_fma_f32 v123, v67, v123, v83
	v_fma_f32 v124, v68, v124, v84
	v_fma_f32 v125, v69, v125, v85
	v_fma_f32 v126, v70, v126, v86
	v_fma_f32 v127, v71, v127, v87
	v_fma_f32 v128, v72, v128, v88
	v_fma_f32 v129, v73, v129, v89
	v_fma_f32 v130, v74, v130, v90
	v_fma_f32 v131, v75, v131, v91
	v_fma_f32 v132, v76, v132, v92
	v_fma_f32 v133, v77, v133, v93
	v_fma_f32 v134, v78, v134, v94
	v_fma_f32 v135, v79, v135, v95
	v_cvt_pk_bf16_f32 v120, v120, v121
	v_cvt_pk_bf16_f32 v121, v122, v123
	v_cvt_pk_bf16_f32 v122, v124, v125
	v_cvt_pk_bf16_f32 v123, v126, v127
	v_cvt_pk_bf16_f32 v124, v128, v129
	v_cvt_pk_bf16_f32 v125, v130, v131
	v_cvt_pk_bf16_f32 v126, v132, v133
	v_cvt_pk_bf16_f32 v127, v134, v135
	global_store_dwordx4 v0, v[120:123], s[12:13]
	global_store_dwordx4 v0, v[124:127], s[12:13] offset:1024
	s_add_i32 s26, s26, s88
	s_cmpk_gt_i32 s26, 0x7fff
	s_cbranch_scc1 .Lp6_done

; __device__ __forceinline__ unsigned cvt_pk_bf16(float lo, float hi) { unsigned r; asm("v_cvt_pk_bf16_f32 %0, %1, %2" : "=v"(r) : "v"(lo), "v"(hi)); return r; }
; __device__ __forceinline__ void norm_apply(const f32x4 (&v)[4], const float* g, const float* sc, const float* sh, bf16_t* orow, int lane) {
;     float s = 0.f;
; #pragma unroll
;     for (int j = 0; j < 4; ++j) s += (v[j][0] * v[j][0] + v[j][1] * v[j][1]) + (v[j][2] * v[j][2] + v[j][3] * v[j][3]);
;     const float rstd = rsqrtf(wave_sum(s) * (1.f / 1024.f) + EPS);
; #pragma unroll
;     for (int j = 0; j < 4; ++j) { const int c4 = lane + 64 * j;
;         const f32x4 gg = *((const f32x4*)g + c4), cc = *((const f32x4*)sc + c4), hh = *((const f32x4*)sh + c4);
;         const f32x4 h = v[j] * rstd * gg * (cc + 1.f) + hh;
;         u32x2 w; w.x = cvt_pk_bf16(h[0], h[1]); w.y = cvt_pk_bf16(h[2], h[3]);
;         *((u32x2*)orow + c4) = w; }
; }
.Lp6_o1_go:
	v_lshlrev_b32_e32 v120, 16, v104
	v_and_b32_e32 v121, 0xffff0000, v104
	v_lshlrev_b32_e32 v122, 16, v105
	v_and_b32_e32 v123, 0xffff0000, v105
	v_lshlrev_b32_e32 v124, 16, v106
	v_and_b32_e32 v125, 0xffff0000, v106
	v_lshlrev_b32_e32 v126, 16, v107
	v_and_b32_e32 v127, 0xffff0000, v107
	v_lshlrev_b32_e32 v128, 16, v108
	v_and_b32_e32 v129, 0xffff0000, v108
	v_lshlrev_b32_e32 v130, 16, v109
	v_and_b32_e32 v131, 0xffff0000, v109
	v_lshlrev_b32_e32 v132, 16, v110
	v_and_b32_e32 v133, 0xffff0000, v110
	v_lshlrev_b32_e32 v134, 16, v111
	v_and_b32_e32 v135, 0xffff0000, v111
	s_add_i32 s22, s26, s88
	s_add_i32 s22, s22, s88
	s_min_i32 s22, s22, 0x7fff
	s_lshl_b32 s0, s22, 11
	s_add_u32 s0, s4, s0
	s_addc_u32 s1, s5, 0
	global_load_dwordx4 v[104:107], v0, s[0:1]
	global_load_dwordx4 v[108:111], v0, s[0:1] offset:1024
	v_mul_f32_e32 v11, v120, v120
	v_mul_f32_e32 v12, v121, v121
	v_fmac_f32_e32 v11, v122, v122
	v_fmac_f32_e32 v12, v123, v123
	v_fmac_f32_e32 v11, v124, v124
	v_fmac_f32_e32 v12, v125, v125
	v_fmac_f32_e32 v11, v126, v126
	v_fmac_f32_e32 v12, v127, v127
	v_fmac_f32_e32 v11, v128, v128
	v_fmac_f32_e32 v12, v129, v129
	v_fmac_f32_e32 v11, v130, v130
	v_fmac_f32_e32 v12, v131, v131
	v_fmac_f32_e32 v11, v132, v132
	v_fmac_f32_e32 v12, v133, v133
	v_fmac_f32_e32 v11, v134, v134
	v_fmac_f32_e32 v12, v135, v135
	v_add_f32_e32 v11, v11, v12
	ds_bpermute_b32 v12, v2, v11
	s_waitcnt lgkmcnt(0)
	v_add_f32_e32 v11, v11, v12
	ds_bpermute_b32 v12, v3, v11
	s_waitcnt lgkmcnt(0)
	v_add_f32_e32 v11, v11, v12
	ds_bpermute_b32 v12, v5, v11
	s_waitcnt lgkmcnt(0)
	v_add_f32_e32 v11, v11, v12
	ds_bpermute_b32 v12, v7, v11
	s_waitcnt lgkmcnt(0)
	v_add_f32_e32 v11, v11, v12
	ds_bpermute_b32 v12, v8, v11
	s_waitcnt lgkmcnt(0)
	v_add_f32_e32 v11, v11, v12
	ds_bpermute_b32 v12, v9, v11
	s_waitcnt lgkmcnt(0)
	v_add_f32_e32 v11, v11, v12
	v_mov_b32_e32 v12, 0x358637bd
	v_fmac_f32_e32 v12, 0x3a800000, v11
	v_rsq_f32_e32 v13, v12
	s_nop 0
	s_lshl_b32 s12, s26, 11
	s_add_u32 s12, s30, s12
	s_addc_u32 s13, s31, 0
	s_add_u32 s12, s12, 0x1d00000
	s_addc_u32 s13, s13, 0
	v_mul_f32_e32 v120, v13, v120
	v_mul_f32_e32 v121, v13, v121
	v_mul_f32_e32 v122, v13, v122
	v_mul_f32_e32 v123, v13, v123
	v_mul_f32_e32 v124, v13, v124
	v_mul_f32_e32 v125, v13, v125
	v_mul_f32_e32 v126, v13, v126
	v_mul_f32_e32 v127, v13, v127
	v_mul_f32_e32 v128, v13, v128
	v_mul_f32_e32 v129, v13, v129
	v_mul_f32_e32 v130, v13, v130
	v_mul_f32_e32 v131, v13, v131
	v_mul_f32_e32 v132, v13, v132
	v_mul_f32_e32 v133, v13, v133
	v_mul_f32_e32 v134, v13, v134
	v_mul_f32_e32 v135, v13, v135
	v_mul_f32_e32 v120, v16, v120
	v_mul_f32_e32 v121, v17, v121
	v_mul_f32_e32 v122, v18, v122
	v_mul_f32_e32 v123, v19, v123
	v_mul_f32_e32 v124, v20, v124
	v_mul_f32_e32 v125, v21, v125
	v_mul_f32_e32 v126, v22, v126
	v_mul_f32_e32 v127, v23, v127
	v_mul_f32_e32 v128, v24, v128
	v_mul_f32_e32 v129, v25, v129
	v_mul_f32_e32 v130, v26, v130
	v_mul_f32_e32 v131, v27, v131
	v_mul_f32_e32 v132, v28, v132
	v_mul_f32_e32 v133, v29, v133
	v_mul_f32_e32 v134, v30, v134
	v_mul_f32_e32 v135, v31, v135
	v_fma_f32 v120, v64, v120, v80
	v_fma_f32 v121, v65, v121, v81
	v_fma_f32 v122, v66, v122, v82
	v_fma_f32 v123, v67, v123, v83
	v_fma_f32 v124, v68, v124, v84
	v_fma_f32 v125, v69, v125, v85
	v_fma_f32 v126, v70, v126, v86
	v_fma_f32 v127, v71, v127, v87
	v_fma_f32 v128, v72, v128, v88
	v_fma_f32 v129, v73, v129, v89
	v_fma_f32 v130, v74, v130, v90
	v_fma_f32 v131, v75, v131, v91
	v_fma_f32 v132, v76, v132, v92
	v_fma_f32 v133, v77, v133, v93
	v_fma_f32 v134, v78, v134, v94
	v_fma_f32 v135, v79, v135, v95
	v_cvt_pk_bf16_f32 v120, v120, v121
	v_cvt_pk_bf16_f32 v121, v122, v123
	v_cvt_pk_bf16_f32 v122, v124, v125
	v_cvt_pk_bf16_f32 v123, v126, v127
	v_cvt_pk_bf16_f32 v124, v128, v129
	v_cvt_pk_bf16_f32 v125, v130, v131
	v_cvt_pk_bf16_f32 v126, v132, v133
	v_cvt_pk_bf16_f32 v127, v134, v135
	global_store_dwordx4 v0, v[120:123], s[12:13]
	global_store_dwordx4 v0, v[124:127], s[12:13] offset:1024
	s_add_i32 s26, s26, s88
	s_cmpk_gt_i32 s26, 0x7fff
	s_cbranch_scc1 .Lp6_done
	s_branch .Lp6_e0

; __device__ __forceinline__ void sample_combine(const float* gate, const float* part, int nsk, int srow, f32x4 (&v)[4], int lane) {
; #pragma unroll
;     for (int j = 0; j < 4; ++j) { const int c4 = lane + 64 * j; f32x4 a = (f32x4){0.f, 0.f, 0.f, 0.f};
;         for (int k = 0; k < nsk; ++k) a += *((const f32x4*)(part + ((size_t)k * 512 + srow) * DM) + c4);
;         v[j] = v[j] + *((const f32x4*)gate + c4) * a; }
; }
; __global__ void __launch_bounds__(512, 2) mega_fwd(Args a) {
;     ...
;         for (int sr = ((bx + 128) % G) * 8 + wid; sr < MS; sr += G * 8) { const int b16 = 8 + (sr >> 6); f32x4 v[4];
;             norm_load(x_s + (size_t)sr * DM, v, lane);
;             sample_combine(MOD + (size_t)b16 * 6144 + 2048, PART, 4, sr, v, lane);
.LBB0_1107:
	v_cmp_lt_i32_e32 vcc, v18, v17
	v_lshl_add_u64 v[6:7], s[14:15], 0, v[0:1]
	v_lshl_add_u64 v[4:5], s[8:9], 0, v[0:1]
	v_cndmask_b32_e32 v25, v16, v18, vcc
	v_cmp_lt_i32_e32 vcc, v19, v17
	global_load_dwordx4 v[26:29], v[6:7], off nt
	global_load_dwordx4 v[30:33], v[6:7], off offset:1024 nt
	global_load_dwordx4 v[34:37], v[6:7], off offset:2048 nt
	global_load_dwordx4 v[38:41], v[6:7], off offset:3072 nt
	v_cndmask_b32_e32 v42, v16, v19, vcc
	v_cmp_lt_i32_e32 vcc, v20, v17
	s_ashr_i32 s10, s0, 6
	s_add_i32 s10, s10, 8
	v_cndmask_b32_e32 v43, v16, v20, vcc
	v_cmp_lt_i32_e32 vcc, v21, v17
	s_mul_hi_i32 s11, s10, 0x6000
	s_mulk_i32 s10, 0x6000
	v_cndmask_b32_e32 v44, v16, v21, vcc
	v_cmp_lt_i32_e32 vcc, v22, v17
	v_lshlrev_b32_e32 v122, 2, v42
	v_lshlrev_b32_e32 v123, 2, v43
	v_cndmask_b32_e32 v45, v16, v22, vcc
	v_cmp_lt_i32_e32 vcc, v23, v17
	v_lshlrev_b32_e32 v124, 2, v44
	v_lshlrev_b32_e32 v125, 2, v45
	v_cndmask_b32_e32 v46, v16, v23, vcc
	v_add_co_u32_e32 v6, vcc, s1, v4
	v_lshlrev_b32_e32 v126, 2, v46
	s_nop 0
	v_addc_co_u32_e32 v7, vcc, 0, v5, vcc
	v_add_co_u32_e32 v74, vcc, s7, v4
	s_add_u32 s33, s30, s10
	s_nop 0
	v_addc_co_u32_e32 v75, vcc, 0, v5, vcc
	v_add_co_u32_e32 v86, vcc, s21, v4
	global_load_dwordx4 v[42:45], v[6:7], off
	global_load_dwordx4 v[46:49], v[6:7], off offset:1024
	global_load_dwordx4 v[50:53], v[6:7], off offset:2048
	global_load_dwordx4 v[54:57], v[6:7], off offset:3072
	v_addc_co_u32_e32 v87, vcc, 0, v5, vcc
	s_addc_u32 s36, s31, s11
	global_load_dwordx4 v[58:61], v[74:75], off
	global_load_dwordx4 v[62:65], v[74:75], off offset:1024
	global_load_dwordx4 v[66:69], v[74:75], off offset:2048
	global_load_dwordx4 v[70:73], v[74:75], off offset:3072
	v_add_co_u32_e32 v98, vcc, s22, v4
	global_load_dwordx4 v[74:77], v[86:87], off
	global_load_dwordx4 v[78:81], v[86:87], off offset:1024
	global_load_dwordx4 v[82:85], v[86:87], off offset:2048
	v_addc_co_u32_e32 v99, vcc, 0, v5, vcc
	global_load_dwordx4 v[4:7], v[86:87], off offset:3072
	s_add_u32 s10, s33, 0x2000
	global_load_dwordx4 v[86:89], v[98:99], off
	global_load_dwordx4 v[90:93], v[98:99], off offset:1024
	global_load_dwordx4 v[94:97], v[98:99], off offset:2048
	s_addc_u32 s11, s36, 0
	global_load_dwordx4 v[98:101], v[98:99], off offset:3072
	s_nop 0
	global_load_dwordx4 v[102:105], v12, s[10:11]
	global_load_dwordx4 v[106:109], v13, s[10:11]
	global_load_dwordx4 v[110:113], v14, s[10:11]
	global_load_dwordx4 v[114:117], v15, s[10:11]
	s_add_i32 s24, s0, 0x8000
	s_ashr_i32 s25, s24, 31
	s_lshl_b64 s[10:11], s[24:25], 11
	s_add_u32 s26, s33, 0x4000
	v_lshl_add_u64 v[118:119], v[2:3], 0, s[10:11]
	s_addc_u32 s27, s36, 0
	v_lshl_add_u64 v[120:121], v[10:11], 0, s[10:11]
	s_add_u32 s10, s33, 0x3000
	s_addc_u32 s11, s36, 0
	v_lshlrev_b32_e32 v25, 2, v25
	s_add_i32 s0, s0, s88
	s_add_u32 s8, s8, s12
	s_addc_u32 s9, s9, s13
	s_add_u32 s14, s14, s12
	s_addc_u32 s15, s15, s13
	s_cmpk_gt_i32 s0, 0x1ff
	s_waitcnt vmcnt(19)
	v_pk_add_f32 v[42:43], v[42:43], 0 op_sel_hi:[1,0]
	v_pk_add_f32 v[44:45], v[44:45], 0 op_sel_hi:[1,0]
	s_waitcnt vmcnt(18)
	v_pk_add_f32 v[46:47], v[46:47], 0 op_sel_hi:[1,0]
	s_waitcnt vmcnt(16)
	v_pk_add_f32 v[54:55], v[54:55], 0 op_sel_hi:[1,0]
	v_pk_add_f32 v[48:49], v[48:49], 0 op_sel_hi:[1,0]
	s_waitcnt vmcnt(15)
	v_pk_add_f32 v[42:43], v[42:43], v[58:59]
	v_pk_add_f32 v[52:53], v[52:53], 0 op_sel_hi:[1,0]
	v_pk_add_f32 v[50:51], v[50:51], 0 op_sel_hi:[1,0]
	v_pk_add_f32 v[56:57], v[56:57], 0 op_sel_hi:[1,0]
	v_pk_add_f32 v[44:45], v[44:45], v[60:61]
	s_waitcnt vmcnt(14)
	v_pk_add_f32 v[46:47], v[46:47], v[62:63]
	s_waitcnt vmcnt(12)
	v_pk_add_f32 v[54:55], v[54:55], v[70:71]
	s_waitcnt vmcnt(11)
	v_pk_add_f32 v[42:43], v[42:43], v[74:75]
	v_pk_add_f32 v[48:49], v[48:49], v[64:65]
	v_pk_add_f32 v[52:53], v[52:53], v[68:69]
	v_pk_add_f32 v[50:51], v[50:51], v[66:67]
	v_pk_add_f32 v[56:57], v[56:57], v[72:73]
	v_pk_add_f32 v[44:45], v[44:45], v[76:77]
	s_waitcnt vmcnt(10)
	v_pk_add_f32 v[46:47], v[46:47], v[78:79]
	s_waitcnt vmcnt(8)
	v_pk_add_f32 v[4:5], v[54:55], v[4:5]
	s_waitcnt vmcnt(7)
	v_pk_add_f32 v[42:43], v[42:43], v[86:87]
	v_pk_add_f32 v[48:49], v[48:49], v[80:81]
	v_pk_add_f32 v[52:53], v[52:53], v[84:85]
	v_pk_add_f32 v[50:51], v[50:51], v[82:83]
	v_pk_add_f32 v[6:7], v[56:57], v[6:7]
	v_pk_add_f32 v[44:45], v[44:45], v[88:89]
	s_waitcnt vmcnt(6)
	v_pk_add_f32 v[46:47], v[46:47], v[90:91]
	s_waitcnt vmcnt(4)
	v_pk_add_f32 v[4:5], v[4:5], v[98:99]
	s_waitcnt vmcnt(3)
	v_pk_fma_f32 v[26:27], v[42:43], v[102:103], v[26:27]
	v_pk_add_f32 v[48:49], v[48:49], v[92:93]
	v_pk_add_f32 v[52:53], v[52:53], v[96:97]
	v_pk_add_f32 v[50:51], v[50:51], v[94:95]
	v_pk_add_f32 v[6:7], v[6:7], v[100:101]
	v_pk_fma_f32 v[28:29], v[44:45], v[104:105], v[28:29]
	s_waitcnt vmcnt(2)
	v_pk_fma_f32 v[30:31], v[46:47], v[106:107], v[30:31]
	s_waitcnt vmcnt(0)
; __device__ __forceinline__ unsigned cvt_pk_bf16(float lo, float hi) { unsigned r; asm("v_cvt_pk_bf16_f32 %0, %1, %2" : "=v"(r) : "v"(lo), "v"(hi)); return r; }
; __device__ __forceinline__ void norm_apply(const f32x4 (&v)[4], const float* g, const float* sc, const float* sh, bf16_t* orow, int lane) {
;     float s = 0.f;
; #pragma unroll
;     for (int j = 0; j < 4; ++j) s += (v[j][0] * v[j][0] + v[j][1] * v[j][1]) + (v[j][2] * v[j][2] + v[j][3] * v[j][3]);
;     const float rstd = rsqrtf(wave_sum(s) * (1.f / 1024.f) + EPS);
; #pragma unroll
;     for (int j = 0; j < 4; ++j) { const int c4 = lane + 64 * j;
;         const f32x4 gg = *((const f32x4*)g + c4), cc = *((const f32x4*)sc + c4), hh = *((const f32x4*)sh + c4);
;         const f32x4 h = v[j] * rstd * gg * (cc + 1.f) + hh;
;         u32x2 w; w.x = cvt_pk_bf16(h[0], h[1]); w.y = cvt_pk_bf16(h[2], h[3]);
;         *((u32x2*)orow + c4) = w; }
; }
; __global__ void __launch_bounds__(512, 2) mega_fwd(Args a) {
;     ...
;             row_store_bf16(X1B + (size_t)(MP + sr) * DM, v, lane);
;             row_load_bf16(X1B + (size_t)(MP + sr) * DM, v, lane);
;             norm_apply(v, norm2_g, MOD + (size_t)b16 * 6144 + 4096, MOD + (size_t)b16 * 6144 + 3072, Hb + (size_t)(MP + sr) * DM, lane);
	v_pk_fma_f32 v[4:5], v[4:5], v[114:115], v[38:39]
	v_cvt_pk_bf16_f32 v26, v26, v27
	v_cvt_pk_bf16_f32 v27, v28, v29
	v_pk_fma_f32 v[32:33], v[48:49], v[108:109], v[32:33]
	v_pk_fma_f32 v[36:37], v[52:53], v[112:113], v[36:37]
	v_pk_fma_f32 v[34:35], v[50:51], v[110:111], v[34:35]
	v_pk_fma_f32 v[6:7], v[6:7], v[116:117], v[40:41]
	v_cvt_pk_bf16_f32 v28, v30, v31
	v_cvt_pk_bf16_f32 v29, v32, v33
	v_cvt_pk_bf16_f32 v30, v34, v35
	v_cvt_pk_bf16_f32 v31, v36, v37
	v_cvt_pk_bf16_f32 v4, v4, v5
	s_nop 0
	v_cvt_pk_bf16_f32 v5, v6, v7
	global_store_dwordx2 v[118:119], v[26:27], off
	global_store_dwordx2 v[118:119], v[28:29], off offset:512
	global_store_dwordx2 v[118:119], v[30:31], off offset:1024
	global_store_dwordx2 v[118:119], v[4:5], off offset:1536
	v_lshlrev_b32_e32 v35, 16, v4
	v_and_b32_e32 v37, 0xffff0000, v4
	v_lshlrev_b32_e32 v38, 16, v5
	v_and_b32_e32 v39, 0xffff0000, v5
	v_lshlrev_b32_e32 v40, 16, v26
	v_and_b32_e32 v41, 0xffff0000, v26
	v_lshlrev_b32_e32 v42, 16, v27
	v_and_b32_e32 v43, 0xffff0000, v27
	v_lshlrev_b32_e32 v45, 16, v29
	v_lshlrev_b32_e32 v44, 16, v28
	v_and_b32_e32 v47, 0xffff0000, v29
	v_and_b32_e32 v46, 0xffff0000, v28
	v_lshlrev_b32_e32 v48, 16, v30
	v_and_b32_e32 v49, 0xffff0000, v30
	v_lshlrev_b32_e32 v50, 16, v31
	v_and_b32_e32 v51, 0xffff0000, v31
	global_load_dwordx4 v[4:7], v[8:9], off
	global_load_dwordx4 v[26:29], v12, s[26:27]
	global_load_dwordx4 v[30:33], v12, s[10:11]
	global_load_dwordx4 v[130:133], v[8:9], off offset:1024
	global_load_dwordx4 v[134:137], v13, s[26:27]
	global_load_dwordx4 v[138:141], v13, s[10:11]
	global_load_dwordx4 v[142:145], v[8:9], off offset:2048
	global_load_dwordx4 v[146:149], v14, s[26:27]
	global_load_dwordx4 v[150:153], v14, s[10:11]
	global_load_dwordx4 v[154:157], v[8:9], off offset:3072
	global_load_dwordx4 v[158:161], v15, s[26:27]
	global_load_dwordx4 v[162:165], v15, s[10:11]
	v_mul_f32_e32 v34, v43, v43
	v_mul_f32_e32 v36, v41, v41
	v_pk_mul_f32 v[52:53], v[46:47], v[46:47]
	v_mov_b32_e32 v55, v35
	v_mul_f32_e32 v54, v49, v49
	v_pk_fma_f32 v[58:59], v[42:43], v[42:43], v[34:35] op_sel_hi:[1,1,0]
	v_pk_fma_f32 v[60:61], v[40:41], v[40:41], v[36:37] op_sel_hi:[1,1,0]
	v_mul_f32_e32 v56, v51, v51
	v_pk_fma_f32 v[52:53], v[44:45], v[44:45], v[52:53]
	v_pk_fma_f32 v[62:63], v[48:49], v[48:49], v[54:55] op_sel_hi:[1,1,0]
	v_mov_b32_e32 v34, v60
	v_mov_b32_e32 v54, v58
	v_mul_f32_e32 v64, v37, v37
	v_mul_f32_e32 v65, v38, v38
	v_mul_f32_e32 v66, v39, v39
	v_pk_fma_f32 v[56:57], v[50:51], v[50:51], v[56:57] op_sel_hi:[1,1,0]
	v_pk_add_f32 v[58:59], v[60:61], v[58:59]
	v_pk_add_f32 v[52:53], v[52:53], v[52:53] op_sel:[0,1] op_sel_hi:[1,0]
	v_pk_mul_f32 v[54:55], v[34:35], v[54:55]
	v_mov_b32_e32 v63, v65
	v_mov_b32_e32 v57, v66
	v_mov_b32_e32 v53, v64
	v_mov_b32_e32 v59, v55
	v_pk_add_f32 v[56:57], v[62:63], v[56:57]
	v_pk_add_f32 v[52:53], v[58:59], v[52:53]
	v_mov_b32_e32 v36, v35
	v_pk_add_f32 v[52:53], v[52:53], v[56:57]
	s_waitcnt vmcnt(10)
	v_pk_add_f32 v[26:27], v[26:27], 1.0 op_sel_hi:[1,0]
	v_add_f32_e32 v34, v52, v53
	ds_bpermute_b32 v25, v25, v34
	v_pk_add_f32 v[28:29], v[28:29], 1.0 op_sel_hi:[1,0]
	s_waitcnt lgkmcnt(0)
	v_add_f32_e32 v25, v34, v25
	ds_bpermute_b32 v34, v122, v25
	s_waitcnt lgkmcnt(0)
	v_add_f32_e32 v25, v25, v34
	ds_bpermute_b32 v34, v123, v25
	s_waitcnt lgkmcnt(0)
	v_add_f32_e32 v25, v25, v34
	ds_bpermute_b32 v34, v124, v25
	s_waitcnt lgkmcnt(0)
	v_add_f32_e32 v25, v25, v34
	ds_bpermute_b32 v34, v125, v25
	s_waitcnt lgkmcnt(0)
	v_add_f32_e32 v25, v25, v34
	ds_bpermute_b32 v34, v126, v25
	s_waitcnt lgkmcnt(0)
	v_add_f32_e32 v25, v25, v34
	v_fmamk_f32 v25, v25, 0x3a800000, v24
	v_mul_f32_e32 v34, 0x4b800000, v25
	v_cmp_gt_f32_e32 vcc, s23, v25
	s_nop 1
	v_cndmask_b32_e32 v25, v25, v34, vcc
	v_rsq_f32_e32 v25, v25
	s_nop 0
	v_mul_f32_e32 v34, 0x45800000, v25
	v_cndmask_b32_e32 v34, v25, v34, vcc
	v_pk_mul_f32 v[40:41], v[34:35], v[40:41] op_sel_hi:[0,1]
	v_pk_mul_f32 v[42:43], v[34:35], v[42:43] op_sel_hi:[0,1]
	v_pk_mul_f32 v[4:5], v[4:5], v[40:41]
	v_pk_mul_f32 v[6:7], v[6:7], v[42:43]
	s_waitcnt vmcnt(9)
	v_pk_fma_f32 v[4:5], v[26:27], v[4:5], v[30:31]
	v_pk_fma_f32 v[6:7], v[28:29], v[6:7], v[32:33]
	v_cvt_pk_bf16_f32 v4, v4, v5
	v_mov_b32_e32 v40, v45
	v_cvt_pk_bf16_f32 v5, v6, v7
	global_store_dwordx2 v[120:121], v[4:5], off
	v_mov_b32_e32 v45, v46
	v_mov_b32_e32 v41, v47
	v_pk_mul_f32 v[42:43], v[34:35], v[44:45] op_sel_hi:[0,1]
	v_pk_mul_f32 v[40:41], v[34:35], v[40:41] op_sel_hi:[0,1]
	v_pk_mul_f32 v[38:39], v[38:39], v[34:35] op_sel_hi:[1,0]
	s_waitcnt vmcnt(9)
	v_pk_mul_f32 v[4:5], v[130:131], v[42:43]
	s_waitcnt vmcnt(8)
	v_pk_add_f32 v[26:27], v[134:135], 1.0 op_sel_hi:[1,0]
	v_pk_mul_f32 v[6:7], v[132:133], v[40:41]
	v_pk_add_f32 v[28:29], v[136:137], 1.0 op_sel_hi:[1,0]
	s_waitcnt vmcnt(7)
	v_pk_fma_f32 v[4:5], v[26:27], v[4:5], v[138:139]
	v_pk_fma_f32 v[6:7], v[28:29], v[6:7], v[140:141]
	v_cvt_pk_bf16_f32 v4, v4, v5
	v_pk_mul_f32 v[42:43], v[34:35], v[48:49] op_sel_hi:[0,1]
	v_cvt_pk_bf16_f32 v5, v6, v7
	global_store_dwordx2 v[120:121], v[4:5], off offset:512
	v_pk_mul_f32 v[40:41], v[34:35], v[50:51] op_sel_hi:[0,1]
	v_pk_mul_f32 v[34:35], v[36:37], v[34:35] op_sel_hi:[1,0]
	s_waitcnt vmcnt(7)
	v_pk_mul_f32 v[4:5], v[142:143], v[42:43]
	s_waitcnt vmcnt(6)
	v_pk_add_f32 v[26:27], v[146:147], 1.0 op_sel_hi:[1,0]
	v_pk_mul_f32 v[6:7], v[144:145], v[40:41]
	v_pk_add_f32 v[28:29], v[148:149], 1.0 op_sel_hi:[1,0]
	s_waitcnt vmcnt(5)
	v_pk_fma_f32 v[4:5], v[4:5], v[26:27], v[150:151]
	v_pk_fma_f32 v[6:7], v[6:7], v[28:29], v[152:153]
	v_cvt_pk_bf16_f32 v4, v4, v5
	s_nop 0
	v_cvt_pk_bf16_f32 v5, v6, v7
	global_store_dwordx2 v[120:121], v[4:5], off offset:1024
	s_waitcnt vmcnt(5)
	v_pk_mul_f32 v[4:5], v[34:35], v[154:155]
	s_waitcnt vmcnt(4)
	v_pk_add_f32 v[26:27], v[158:159], 1.0 op_sel_hi:[1,0]
	v_pk_mul_f32 v[6:7], v[38:39], v[156:157]
	v_pk_add_f32 v[28:29], v[160:161], 1.0 op_sel_hi:[1,0]
	s_waitcnt vmcnt(3)
	v_pk_fma_f32 v[4:5], v[4:5], v[26:27], v[162:163]
	v_pk_fma_f32 v[6:7], v[6:7], v[28:29], v[164:165]
	v_cvt_pk_bf16_f32 v4, v4, v5
	s_nop 0
	v_cvt_pk_bf16_f32 v5, v6, v7
	global_store_dwordx2 v[120:121], v[4:5], off offset:1536
	s_cbranch_scc0 .LBB0_1107
